# v45
# speedup vs baseline: 1.0085x; 1.0085x over previous
.LBB0_479:
	s_or_b64 exec, exec, s[12:13]
	s_bitcmp1_b32 s31, 0
	v_and_b32_e32 v32, 64, v104
	s_cselect_b32 s12, 0x5180, 0
	v_add_u32_e32 v43, 64, v32
	v_xor_b32_e32 v32, 32, v104
	v_add_u32_e32 v37, s12, v72
	v_cmp_lt_i32_e64 s[12:13], v32, v43
	s_waitcnt vmcnt(47)
	v_lshlrev_b32_e32 v33, 16, v106
	s_waitcnt vmcnt(43)
	v_lshlrev_b32_e32 v34, 16, v112
	v_cndmask_b32_e64 v32, v104, v32, s[12:13]
	v_lshlrev_b32_e32 v38, 2, v32
	s_waitcnt vmcnt(40)
	v_lshlrev_b32_e32 v32, 16, v113
	v_sub_f32_e32 v32, 1.0, v32
	v_mul_f32_e32 v45, v32, v44
	v_rcp_f32_e32 v32, v45
	v_mul_f32_e32 v50, v45, v33
	v_add_f32_e32 v33, -1.0, v34
	v_lshlrev_b32_e32 v46, 16, v111
	v_lshlrev_b32_e32 v35, 16, v108
	s_waitcnt vmcnt(0)
	v_fma_f32 v47, v105, v33, 1.0
	v_pk_mul_f32 v[34:35], v[46:47], v[34:35]
	v_xor_b32_e32 v39, 16, v104
	v_pk_mul_f32 v[158:159], v[34:35], v[32:33] op_sel_hi:[1,0]
	v_cmp_lt_i32_e64 s[12:13], v39, v43
	v_pk_mul_f32 v[32:33], v[50:51], v[158:159] op_sel_hi:[0,1]
	ds_bpermute_b32 v32, v38, v32
	ds_bpermute_b32 v33, v38, v33
	v_cndmask_b32_e64 v34, v104, v39, s[12:13]
	v_lshlrev_b32_e32 v39, 2, v34
	v_xor_b32_e32 v40, 8, v104
	v_cmp_lt_i32_e64 s[12:13], v40, v43
	s_waitcnt lgkmcnt(0)
	v_pk_fma_f32 v[32:33], v[50:51], v[158:159], v[32:33] op_sel_hi:[0,1,1]
	ds_bpermute_b32 v34, v39, v32
	ds_bpermute_b32 v35, v39, v33
	v_cndmask_b32_e64 v40, v104, v40, s[12:13]
	v_lshlrev_b32_e32 v40, 2, v40
	v_xor_b32_e32 v41, 4, v104
	v_cmp_lt_i32_e64 s[12:13], v41, v43
	s_waitcnt lgkmcnt(0)
	v_pk_add_f32 v[32:33], v[32:33], v[34:35]
	s_nop 1
	v_add_f32_dpp v32, v32, v32 row_ror:8 row_mask:0xf bank_mask:0xf
	v_add_f32_dpp v33, v33, v33 row_ror:8 row_mask:0xf bank_mask:0xf
	v_cndmask_b32_e64 v41, v104, v41, s[12:13]
	v_lshlrev_b32_e32 v41, 2, v41
	v_xor_b32_e32 v42, 2, v104
	v_cmp_lt_i32_e64 s[12:13], v42, v43
	s_waitcnt lgkmcnt(0)
	s_nop 1
	v_add_f32_dpp v32, v32, v32 row_ror:4 row_mask:0xf bank_mask:0xf
	v_add_f32_dpp v33, v33, v33 row_ror:4 row_mask:0xf bank_mask:0xf
	v_cndmask_b32_e64 v42, v104, v42, s[12:13]
	v_lshlrev_b32_e32 v42, 2, v42
	v_xor_b32_e32 v47, 1, v104
	v_cmp_lt_i32_e64 s[12:13], v47, v43
	s_waitcnt lgkmcnt(0)
	s_nop 1
	v_add_f32_dpp v32, v32, v32 quad_perm:[2,3,0,1] row_mask:0xf bank_mask:0xf
	v_add_f32_dpp v33, v33, v33 quad_perm:[2,3,0,1] row_mask:0xf bank_mask:0xf
	v_cndmask_b32_e64 v43, v104, v47, s[12:13]
	v_lshlrev_b32_e32 v43, 2, v43
	v_lshl_add_u32 v36, v48, 2, v37
	v_lshlrev_b32_e32 v47, 16, v110
	s_waitcnt lgkmcnt(0)
	s_nop 1
	v_add_f32_dpp v32, v32, v32 quad_perm:[1,0,3,2] row_mask:0xf bank_mask:0xf
	v_add_f32_dpp v33, v33, v33 quad_perm:[1,0,3,2] row_mask:0xf bank_mask:0xf
	v_add_u32_e32 v59, v36, v92
	v_mul_f32_e64 v44, v44, -v46
	ds_write_b32 v59, v47 offset:1024
	ds_write2st64_b32 v59, v44, v158 offset1:1
	ds_write2st64_b32 v59, v159, v50 offset0:2 offset1:3
	s_and_saveexec_b64 s[12:13], s[4:5]
	s_cbranch_execz .LBB0_481
	s_waitcnt lgkmcnt(3)
	v_add_u32_e32 v34, v37, v93
	ds_write_b64 v34, v[32:33] offset:20736
.LBB0_481:
	s_or_b64 exec, exec, s[12:13]
	v_lshlrev_b32_e32 v32, 16, v121
	v_sub_f32_e32 v32, 1.0, v32
	v_mul_f32_e32 v46, v32, v45
	v_lshlrev_b32_e32 v33, 16, v107
	v_rcp_f32_e32 v32, v46
	s_waitcnt lgkmcnt(4)
	v_lshlrev_b32_e32 v34, 16, v120
	v_mul_f32_e32 v50, v46, v33
	v_add_f32_e32 v33, -1.0, v34
	v_lshlrev_b32_e32 v158, 16, v118
	s_waitcnt lgkmcnt(3)
	v_lshlrev_b32_e32 v35, 16, v109
	v_fma_f32 v159, v105, v33, 1.0
	v_pk_mul_f32 v[34:35], v[158:159], v[34:35]
	v_lshlrev_b32_e32 v47, 16, v116
	v_pk_mul_f32 v[162:163], v[34:35], v[32:33] op_sel_hi:[1,0]
	v_add_u32_e32 v44, v36, v94
	v_pk_mul_f32 v[32:33], v[50:51], v[162:163] op_sel_hi:[0,1]
	ds_bpermute_b32 v32, v38, v32
	ds_bpermute_b32 v33, v38, v33
	v_mul_f32_e64 v45, v45, -v158
	ds_write_b32 v44, v47 offset:1024
	ds_write2st64_b32 v44, v45, v162 offset1:1
	ds_write2st64_b32 v44, v163, v50 offset0:2 offset1:3
	s_waitcnt lgkmcnt(3)
	v_pk_fma_f32 v[32:33], v[50:51], v[162:163], v[32:33] op_sel_hi:[0,1,1]
	ds_bpermute_b32 v34, v39, v32
	ds_bpermute_b32 v35, v39, v33
	s_waitcnt lgkmcnt(0)
	v_pk_add_f32 v[32:33], v[32:33], v[34:35]
	s_nop 1
	v_add_f32_dpp v32, v32, v32 row_ror:8 row_mask:0xf bank_mask:0xf
	v_add_f32_dpp v33, v33, v33 row_ror:8 row_mask:0xf bank_mask:0xf
	s_waitcnt lgkmcnt(0)
	s_nop 1
	v_add_f32_dpp v32, v32, v32 row_ror:4 row_mask:0xf bank_mask:0xf
	v_add_f32_dpp v33, v33, v33 row_ror:4 row_mask:0xf bank_mask:0xf
	s_waitcnt lgkmcnt(0)
	s_nop 1
	v_add_f32_dpp v32, v32, v32 quad_perm:[2,3,0,1] row_mask:0xf bank_mask:0xf
	v_add_f32_dpp v33, v33, v33 quad_perm:[2,3,0,1] row_mask:0xf bank_mask:0xf
	s_waitcnt lgkmcnt(0)
	s_nop 1
	v_add_f32_dpp v32, v32, v32 quad_perm:[1,0,3,2] row_mask:0xf bank_mask:0xf
	v_add_f32_dpp v33, v33, v33 quad_perm:[1,0,3,2] row_mask:0xf bank_mask:0xf
	s_and_saveexec_b64 s[12:13], s[4:5]
	s_cbranch_execz .LBB0_483
	s_waitcnt lgkmcnt(0)
	v_add_u32_e32 v34, v37, v95
	ds_write_b64 v34, v[32:33] offset:20736
.LBB0_483:
	s_or_b64 exec, exec, s[12:13]
	v_lshlrev_b32_e32 v32, 16, v129
	v_sub_f32_e32 v32, 1.0, v32
	v_mul_f32_e32 v45, v32, v46
	v_lshlrev_b32_e32 v33, 16, v114
	v_rcp_f32_e32 v32, v45
	s_waitcnt lgkmcnt(1)
	v_lshlrev_b32_e32 v34, 16, v126
	v_mul_f32_e32 v50, v45, v33
	v_add_f32_e32 v33, -1.0, v34
	v_lshlrev_b32_e32 v158, 16, v119
	s_waitcnt lgkmcnt(0)
	v_lshlrev_b32_e32 v35, 16, v115
	v_fma_f32 v159, v105, v33, 1.0
	v_pk_mul_f32 v[34:35], v[158:159], v[34:35]
	v_lshlrev_b32_e32 v47, 16, v117
	v_pk_mul_f32 v[162:163], v[34:35], v[32:33] op_sel_hi:[1,0]
	v_mul_f32_e64 v46, v46, -v158
	v_pk_mul_f32 v[32:33], v[50:51], v[162:163] op_sel_hi:[0,1]
	ds_bpermute_b32 v32, v38, v32
	ds_bpermute_b32 v33, v38, v33
	ds_write_b32 v44, v47 offset:2304
	ds_write2st64_b32 v44, v46, v162 offset0:5 offset1:6
	ds_write2st64_b32 v44, v163, v50 offset0:7 offset1:8
	s_waitcnt lgkmcnt(3)
	v_pk_fma_f32 v[32:33], v[50:51], v[162:163], v[32:33] op_sel_hi:[0,1,1]
	ds_bpermute_b32 v34, v39, v32
	ds_bpermute_b32 v35, v39, v33
	s_waitcnt lgkmcnt(0)
	v_pk_add_f32 v[32:33], v[32:33], v[34:35]
	s_nop 1
	v_add_f32_dpp v32, v32, v32 row_ror:8 row_mask:0xf bank_mask:0xf
	v_add_f32_dpp v33, v33, v33 row_ror:8 row_mask:0xf bank_mask:0xf
	s_waitcnt lgkmcnt(0)
	s_nop 1
	v_add_f32_dpp v32, v32, v32 row_ror:4 row_mask:0xf bank_mask:0xf
	v_add_f32_dpp v33, v33, v33 row_ror:4 row_mask:0xf bank_mask:0xf
	s_waitcnt lgkmcnt(0)
	s_nop 1
	v_add_f32_dpp v32, v32, v32 quad_perm:[2,3,0,1] row_mask:0xf bank_mask:0xf
	v_add_f32_dpp v33, v33, v33 quad_perm:[2,3,0,1] row_mask:0xf bank_mask:0xf
	s_waitcnt lgkmcnt(0)
	s_nop 1
	v_add_f32_dpp v32, v32, v32 quad_perm:[1,0,3,2] row_mask:0xf bank_mask:0xf
	v_add_f32_dpp v33, v33, v33 quad_perm:[1,0,3,2] row_mask:0xf bank_mask:0xf
	s_and_saveexec_b64 s[12:13], s[4:5]
	s_cbranch_execz .LBB0_485
	s_waitcnt lgkmcnt(0)
	v_add_u32_e32 v34, v37, v96
	ds_write_b64 v34, v[32:33] offset:20736
.LBB0_485:
	s_or_b64 exec, exec, s[12:13]
	v_lshlrev_b32_e32 v32, 16, v128
	v_sub_f32_e32 v32, 1.0, v32
	v_mul_f32_e32 v46, v32, v45
	v_lshlrev_b32_e32 v33, 16, v122
	v_rcp_f32_e32 v32, v46
	s_waitcnt lgkmcnt(1)
	v_lshlrev_b32_e32 v34, 16, v127
	v_mul_f32_e32 v50, v46, v33
	v_add_f32_e32 v33, -1.0, v34
	v_lshlrev_b32_e32 v158, 16, v125
	s_waitcnt lgkmcnt(0)
	v_lshlrev_b32_e32 v35, 16, v123
	v_fma_f32 v159, v105, v33, 1.0
	v_pk_mul_f32 v[34:35], v[158:159], v[34:35]
	v_lshlrev_b32_e32 v47, 16, v124
	v_pk_mul_f32 v[162:163], v[34:35], v[32:33] op_sel_hi:[1,0]
	v_mul_f32_e64 v45, v45, -v158
	v_pk_mul_f32 v[32:33], v[50:51], v[162:163] op_sel_hi:[0,1]
	ds_bpermute_b32 v32, v38, v32
	ds_bpermute_b32 v33, v38, v33
	ds_write_b32 v44, v47 offset:3584
	ds_write2st64_b32 v44, v45, v162 offset0:10 offset1:11
	ds_write2st64_b32 v44, v163, v50 offset0:12 offset1:13
	s_waitcnt lgkmcnt(3)
	v_pk_fma_f32 v[32:33], v[50:51], v[162:163], v[32:33] op_sel_hi:[0,1,1]
	ds_bpermute_b32 v34, v39, v32
	ds_bpermute_b32 v35, v39, v33
	s_waitcnt lgkmcnt(0)
	v_pk_add_f32 v[32:33], v[32:33], v[34:35]
	s_nop 1
	v_add_f32_dpp v32, v32, v32 row_ror:8 row_mask:0xf bank_mask:0xf
	v_add_f32_dpp v33, v33, v33 row_ror:8 row_mask:0xf bank_mask:0xf
	s_waitcnt lgkmcnt(0)
	s_nop 1
	v_add_f32_dpp v32, v32, v32 row_ror:4 row_mask:0xf bank_mask:0xf
	v_add_f32_dpp v33, v33, v33 row_ror:4 row_mask:0xf bank_mask:0xf
	s_waitcnt lgkmcnt(0)
	s_nop 1
	v_add_f32_dpp v32, v32, v32 quad_perm:[2,3,0,1] row_mask:0xf bank_mask:0xf
	v_add_f32_dpp v33, v33, v33 quad_perm:[2,3,0,1] row_mask:0xf bank_mask:0xf
	s_waitcnt lgkmcnt(0)
	s_nop 1
	v_add_f32_dpp v32, v32, v32 quad_perm:[1,0,3,2] row_mask:0xf bank_mask:0xf
	v_add_f32_dpp v33, v33, v33 quad_perm:[1,0,3,2] row_mask:0xf bank_mask:0xf
	s_and_saveexec_b64 s[12:13], s[4:5]
	s_cbranch_execz .LBB0_487
	s_waitcnt lgkmcnt(0)
	v_add_u32_e32 v34, v37, v97
	ds_write_b64 v34, v[32:33] offset:20736
.LBB0_487:
	s_or_b64 exec, exec, s[12:13]
	v_lshlrev_b32_e32 v32, 16, v137
	v_sub_f32_e32 v32, 1.0, v32
	v_mul_f32_e32 v45, v32, v46
	v_lshlrev_b32_e32 v33, 16, v130
	v_rcp_f32_e32 v32, v45
	s_waitcnt lgkmcnt(1)
	v_lshlrev_b32_e32 v34, 16, v136
	v_mul_f32_e32 v50, v45, v33
	v_add_f32_e32 v33, -1.0, v34
	v_lshlrev_b32_e32 v158, 16, v135
	s_waitcnt lgkmcnt(0)
	v_lshlrev_b32_e32 v35, 16, v132
	v_fma_f32 v159, v105, v33, 1.0
	v_pk_mul_f32 v[34:35], v[158:159], v[34:35]
	v_lshlrev_b32_e32 v47, 16, v134
	v_pk_mul_f32 v[162:163], v[34:35], v[32:33] op_sel_hi:[1,0]
	v_mul_f32_e64 v46, v46, -v158
	v_pk_mul_f32 v[32:33], v[50:51], v[162:163] op_sel_hi:[0,1]
	ds_bpermute_b32 v32, v38, v32
	ds_bpermute_b32 v33, v38, v33
	ds_write_b32 v44, v47 offset:4864
	ds_write2st64_b32 v44, v46, v162 offset0:15 offset1:16
	ds_write2st64_b32 v44, v163, v50 offset0:17 offset1:18
	s_waitcnt lgkmcnt(3)
	v_pk_fma_f32 v[32:33], v[50:51], v[162:163], v[32:33] op_sel_hi:[0,1,1]
	ds_bpermute_b32 v34, v39, v32
	ds_bpermute_b32 v35, v39, v33
	s_waitcnt lgkmcnt(0)
	v_pk_add_f32 v[32:33], v[32:33], v[34:35]
	s_nop 1
	v_add_f32_dpp v32, v32, v32 row_ror:8 row_mask:0xf bank_mask:0xf
	v_add_f32_dpp v33, v33, v33 row_ror:8 row_mask:0xf bank_mask:0xf
	s_waitcnt lgkmcnt(0)
	s_nop 1
	v_add_f32_dpp v32, v32, v32 row_ror:4 row_mask:0xf bank_mask:0xf
	v_add_f32_dpp v33, v33, v33 row_ror:4 row_mask:0xf bank_mask:0xf
	s_waitcnt lgkmcnt(0)
	s_nop 1
	v_add_f32_dpp v32, v32, v32 quad_perm:[2,3,0,1] row_mask:0xf bank_mask:0xf
	v_add_f32_dpp v33, v33, v33 quad_perm:[2,3,0,1] row_mask:0xf bank_mask:0xf
	s_waitcnt lgkmcnt(0)
	s_nop 1
	v_add_f32_dpp v32, v32, v32 quad_perm:[1,0,3,2] row_mask:0xf bank_mask:0xf
	v_add_f32_dpp v33, v33, v33 quad_perm:[1,0,3,2] row_mask:0xf bank_mask:0xf
	s_and_saveexec_b64 s[12:13], s[4:5]
	s_cbranch_execz .LBB0_489
	s_waitcnt lgkmcnt(0)
	v_add_u32_e32 v34, v37, v98
	ds_write_b64 v34, v[32:33] offset:20736
.LBB0_489:
	s_or_b64 exec, exec, s[12:13]
	v_lshlrev_b32_e32 v32, 16, v145
	v_sub_f32_e32 v32, 1.0, v32
	v_mul_f32_e32 v46, v32, v45
	v_lshlrev_b32_e32 v33, 16, v131
	v_rcp_f32_e32 v32, v46
	s_waitcnt lgkmcnt(1)
	v_lshlrev_b32_e32 v34, 16, v144
	v_mul_f32_e32 v50, v46, v33
	v_add_f32_e32 v33, -1.0, v34
	v_lshlrev_b32_e32 v158, 16, v142
	s_waitcnt lgkmcnt(0)
	v_lshlrev_b32_e32 v35, 16, v133
	v_fma_f32 v159, v105, v33, 1.0
	v_pk_mul_f32 v[34:35], v[158:159], v[34:35]
	v_lshlrev_b32_e32 v47, 16, v140
	v_pk_mul_f32 v[162:163], v[34:35], v[32:33] op_sel_hi:[1,0]
	v_mul_f32_e64 v45, v45, -v158
	v_pk_mul_f32 v[32:33], v[50:51], v[162:163] op_sel_hi:[0,1]
	ds_bpermute_b32 v32, v38, v32
	ds_bpermute_b32 v33, v38, v33
	ds_write_b32 v44, v47 offset:6144
	ds_write2st64_b32 v44, v45, v162 offset0:20 offset1:21
	ds_write2st64_b32 v44, v163, v50 offset0:22 offset1:23
	s_waitcnt lgkmcnt(3)
	v_pk_fma_f32 v[32:33], v[50:51], v[162:163], v[32:33] op_sel_hi:[0,1,1]
	ds_bpermute_b32 v34, v39, v32
	ds_bpermute_b32 v35, v39, v33
	s_waitcnt lgkmcnt(0)
	v_pk_add_f32 v[32:33], v[32:33], v[34:35]
	s_nop 1
	v_add_f32_dpp v32, v32, v32 row_ror:8 row_mask:0xf bank_mask:0xf
	v_add_f32_dpp v33, v33, v33 row_ror:8 row_mask:0xf bank_mask:0xf
	s_waitcnt lgkmcnt(0)
	s_nop 1
	v_add_f32_dpp v32, v32, v32 row_ror:4 row_mask:0xf bank_mask:0xf
	v_add_f32_dpp v33, v33, v33 row_ror:4 row_mask:0xf bank_mask:0xf
	s_waitcnt lgkmcnt(0)
	s_nop 1
	v_add_f32_dpp v32, v32, v32 quad_perm:[2,3,0,1] row_mask:0xf bank_mask:0xf
	v_add_f32_dpp v33, v33, v33 quad_perm:[2,3,0,1] row_mask:0xf bank_mask:0xf
	s_waitcnt lgkmcnt(0)
	s_nop 1
	v_add_f32_dpp v32, v32, v32 quad_perm:[1,0,3,2] row_mask:0xf bank_mask:0xf
	v_add_f32_dpp v33, v33, v33 quad_perm:[1,0,3,2] row_mask:0xf bank_mask:0xf
	s_and_saveexec_b64 s[12:13], s[4:5]
	s_cbranch_execz .LBB0_491
	s_waitcnt lgkmcnt(0)
	v_add_u32_e32 v34, v37, v99
	ds_write_b64 v34, v[32:33] offset:20736
.LBB0_491:
	s_or_b64 exec, exec, s[12:13]
	v_lshlrev_b32_e32 v32, 16, v153
	v_sub_f32_e32 v32, 1.0, v32
	v_mul_f32_e32 v45, v32, v46
	v_lshlrev_b32_e32 v33, 16, v138
	v_rcp_f32_e32 v32, v45
	s_waitcnt lgkmcnt(1)
	v_lshlrev_b32_e32 v34, 16, v150
	v_mul_f32_e32 v50, v45, v33
	v_add_f32_e32 v33, -1.0, v34
	v_lshlrev_b32_e32 v158, 16, v143
	s_waitcnt lgkmcnt(0)
	v_lshlrev_b32_e32 v35, 16, v139
	v_fma_f32 v159, v105, v33, 1.0
	v_pk_mul_f32 v[34:35], v[158:159], v[34:35]
	v_lshlrev_b32_e32 v47, 16, v141
	v_pk_mul_f32 v[162:163], v[34:35], v[32:33] op_sel_hi:[1,0]
	v_mul_f32_e64 v46, v46, -v158
	v_pk_mul_f32 v[32:33], v[50:51], v[162:163] op_sel_hi:[0,1]
	ds_bpermute_b32 v32, v38, v32
	ds_bpermute_b32 v33, v38, v33
	ds_write_b32 v44, v47 offset:7424
	ds_write2st64_b32 v44, v46, v162 offset0:25 offset1:26
	ds_write2st64_b32 v44, v163, v50 offset0:27 offset1:28
	s_waitcnt lgkmcnt(3)
	v_pk_fma_f32 v[32:33], v[50:51], v[162:163], v[32:33] op_sel_hi:[0,1,1]
	ds_bpermute_b32 v34, v39, v32
	ds_bpermute_b32 v35, v39, v33
	s_waitcnt lgkmcnt(0)
	v_pk_add_f32 v[32:33], v[32:33], v[34:35]
	s_nop 1
	v_add_f32_dpp v32, v32, v32 row_ror:8 row_mask:0xf bank_mask:0xf
	v_add_f32_dpp v33, v33, v33 row_ror:8 row_mask:0xf bank_mask:0xf
	s_waitcnt lgkmcnt(0)
	s_nop 1
	v_add_f32_dpp v32, v32, v32 row_ror:4 row_mask:0xf bank_mask:0xf
	v_add_f32_dpp v33, v33, v33 row_ror:4 row_mask:0xf bank_mask:0xf
	s_waitcnt lgkmcnt(0)
	s_nop 1
	v_add_f32_dpp v32, v32, v32 quad_perm:[2,3,0,1] row_mask:0xf bank_mask:0xf
	v_add_f32_dpp v33, v33, v33 quad_perm:[2,3,0,1] row_mask:0xf bank_mask:0xf
	s_waitcnt lgkmcnt(0)
	s_nop 1
	v_add_f32_dpp v32, v32, v32 quad_perm:[1,0,3,2] row_mask:0xf bank_mask:0xf
	v_add_f32_dpp v33, v33, v33 quad_perm:[1,0,3,2] row_mask:0xf bank_mask:0xf
	s_and_saveexec_b64 s[12:13], s[4:5]
	s_cbranch_execz .LBB0_493
	s_waitcnt lgkmcnt(0)
	v_add_u32_e32 v34, v37, v100
	ds_write_b64 v34, v[32:33] offset:20736
.LBB0_493:
	s_or_b64 exec, exec, s[12:13]
	v_lshlrev_b32_e32 v32, 16, v152
	v_sub_f32_e32 v32, 1.0, v32
	v_mul_f32_e32 v46, v32, v45
	v_lshlrev_b32_e32 v33, 16, v146
	v_rcp_f32_e32 v32, v46
	s_waitcnt lgkmcnt(1)
	v_lshlrev_b32_e32 v34, 16, v151
	v_mul_f32_e32 v50, v46, v33
	v_add_f32_e32 v33, -1.0, v34
	v_lshlrev_b32_e32 v158, 16, v149
	s_waitcnt lgkmcnt(0)
	v_lshlrev_b32_e32 v35, 16, v147
	v_fma_f32 v159, v105, v33, 1.0
	v_pk_mul_f32 v[34:35], v[158:159], v[34:35]
	s_nop 0
	v_pk_mul_f32 v[162:163], v[34:35], v[32:33] op_sel_hi:[1,0]
	s_nop 0
	v_pk_mul_f32 v[32:33], v[50:51], v[162:163] op_sel_hi:[0,1]
	ds_bpermute_b32 v32, v38, v32
	ds_bpermute_b32 v33, v38, v33
	v_lshlrev_b32_e32 v38, 16, v148
	s_waitcnt lgkmcnt(0)
	v_pk_fma_f32 v[32:33], v[50:51], v[162:163], v[32:33] op_sel_hi:[0,1,1]
	ds_bpermute_b32 v34, v39, v32
	ds_bpermute_b32 v35, v39, v33
	v_mul_f32_e64 v39, v45, -v158
	ds_write_b32 v44, v38 offset:8704
	ds_write2st64_b32 v44, v39, v162 offset0:30 offset1:31
	ds_write2st64_b32 v44, v163, v50 offset0:32 offset1:33
	s_waitcnt lgkmcnt(3)
	v_pk_add_f32 v[32:33], v[32:33], v[34:35]
	s_nop 1
	v_add_f32_dpp v32, v32, v32 row_ror:8 row_mask:0xf bank_mask:0xf
	v_add_f32_dpp v33, v33, v33 row_ror:8 row_mask:0xf bank_mask:0xf
	s_waitcnt lgkmcnt(0)
	s_nop 1
	v_add_f32_dpp v32, v32, v32 row_ror:4 row_mask:0xf bank_mask:0xf
	v_add_f32_dpp v33, v33, v33 row_ror:4 row_mask:0xf bank_mask:0xf
	s_waitcnt lgkmcnt(0)
	s_nop 1
	v_add_f32_dpp v32, v32, v32 quad_perm:[2,3,0,1] row_mask:0xf bank_mask:0xf
	v_add_f32_dpp v33, v33, v33 quad_perm:[2,3,0,1] row_mask:0xf bank_mask:0xf
	s_waitcnt lgkmcnt(0)
	s_nop 1
	v_add_f32_dpp v32, v32, v32 quad_perm:[1,0,3,2] row_mask:0xf bank_mask:0xf
	v_add_f32_dpp v33, v33, v33 quad_perm:[1,0,3,2] row_mask:0xf bank_mask:0xf
	s_and_saveexec_b64 s[12:13], s[4:5]
	s_cbranch_execz .LBB0_496
	s_waitcnt lgkmcnt(0)
	v_add_u32_e32 v34, v37, v101
	ds_write_b64 v34, v[32:33] offset:20736
	s_or_b64 exec, exec, s[12:13]
	s_and_saveexec_b64 s[12:13], s[10:11]
	s_cbranch_execnz .LBB0_497
